# GLA chunk loop: next-chunk load addresses via SGPR row base + 3 per-lane offsets instead of 100 64-bit VALU address ops; plus Down epilogue pipelining
# baseline (speedup 1.0000x reference)
.LBB0_1324:
	v_readfirstlane_b32 s62, v42
	v_readfirstlane_b32 s63, v43
	s_and_b64 s[72:73], s[70:71], exec
	s_cselect_b32 s31, 0, 0xffffffd0
	s_cselect_b32 s11, 0, 0xffffffc1
	v_subrev_u32_e32 v18, s31, v139
	v_subrev_u32_e32 v19, s11, v141
	v_lshlrev_b32_e32 v18, 13, v18
	v_lshlrev_b32_e32 v19, 13, v19
	v_subrev_u32_e32 v20, s62, v46
	v_subrev_u32_e32 v21, s62, v44
	v_add_u32_e32 v20, v20, v18
	v_add_u32_e32 v21, v21, v18
	v_add_u32_e32 v18, v18, v42
	v_add_u32_e32 v19, v19, v48
	v_subrev_u32_e32 v18, s62, v18
	v_subrev_u32_e32 v19, s62, v19
	s_add_i32 s31, s10, s31
	s_lshl_b32 s31, s31, 13
	s_add_u32 s62, s62, s31
	s_addc_u32 s63, s63, 0
	s_and_b64 s[72:73], s[70:71], exec
	s_mov_b32 s72, 0x2000
	s_cselect_b32 s72, s72, 0xffffe000
	s_cselect_b32 s73, 0, -1
	global_load_dword v115, v20, s[62:63]
	global_load_dword v116, v21, s[62:63]
	global_load_dword v118, v18, s[62:63]
	s_add_u32 s62, s62, s72
	s_addc_u32 s63, s63, s73
	global_load_dword v119, v20, s[62:63]
	global_load_dword v121, v21, s[62:63]
	global_load_dword v122, v18, s[62:63]
	s_add_u32 s62, s62, s72
	s_addc_u32 s63, s63, s73
	global_load_dword v124, v20, s[62:63]
	global_load_dword v127, v21, s[62:63]
	global_load_dword v130, v18, s[62:63]
	s_add_u32 s62, s62, s72
	s_addc_u32 s63, s63, s73
	global_load_dword v132, v20, s[62:63]
	global_load_dword v133, v21, s[62:63]
	global_load_dword v135, v18, s[62:63]
	s_add_u32 s62, s62, s72
	s_addc_u32 s63, s63, s73
	global_load_dword v136, v20, s[62:63]
	global_load_dword v137, v21, s[62:63]
	global_load_dword v138, v18, s[62:63]
	s_add_u32 s62, s62, s72
	s_addc_u32 s63, s63, s73
	global_load_dword v143, v20, s[62:63]
	global_load_dword v144, v21, s[62:63]
	global_load_dword v145, v18, s[62:63]
	s_add_u32 s62, s62, s72
	s_addc_u32 s63, s63, s73
	global_load_dword v146, v20, s[62:63]
	global_load_dword v147, v21, s[62:63]
	global_load_dword v148, v18, s[62:63]
	s_add_u32 s62, s62, s72
	s_addc_u32 s63, s63, s73
	global_load_dword v149, v20, s[62:63]
	global_load_dword v150, v21, s[62:63]
	global_load_dword v151, v18, s[62:63]
	s_add_u32 s62, s62, s72
	s_addc_u32 s63, s63, s73
	global_load_dword v152, v20, s[62:63]
	global_load_dword v153, v21, s[62:63]
	global_load_dword v154, v18, s[62:63]
	s_add_u32 s62, s62, s72
	s_addc_u32 s63, s63, s73
	global_load_dword v155, v20, s[62:63]
	global_load_dword v156, v21, s[62:63]
	global_load_dword v157, v18, s[62:63]
	s_add_u32 s62, s62, s72
	s_addc_u32 s63, s63, s73
	global_load_dword v158, v20, s[62:63]
	global_load_dword v159, v21, s[62:63]
	global_load_dword v160, v18, s[62:63]
	s_add_u32 s62, s62, s72
	s_addc_u32 s63, s63, s73
	global_load_dword v161, v20, s[62:63]
	global_load_dword v162, v21, s[62:63]
	global_load_dword v163, v18, s[62:63]
	s_add_u32 s62, s62, s72
	s_addc_u32 s63, s63, s73
	global_load_dword v164, v20, s[62:63]
	global_load_dword v165, v21, s[62:63]
	global_load_dword v166, v18, s[62:63]
	s_add_u32 s62, s62, s72
	s_addc_u32 s63, s63, s73
	global_load_dword v167, v20, s[62:63]
	global_load_dword v168, v21, s[62:63]
	global_load_dword v169, v18, s[62:63]
	s_add_u32 s62, s62, s72
	s_addc_u32 s63, s63, s73
	global_load_dword v170, v20, s[62:63]
	global_load_dword v171, v21, s[62:63]
	global_load_dword v172, v18, s[62:63]
	s_add_u32 s62, s62, s72
	s_addc_u32 s63, s63, s73
	global_load_dword v173, v20, s[62:63]
	global_load_dword v174, v21, s[62:63]
	global_load_dword v175, v18, s[62:63]
	s_and_b64 s[72:73], s[70:71], exec
	s_cselect_b32 s72, 0xfffe2000, 0
	s_cselect_b32 s73, -1, 0
	s_add_u32 s62, s62, s72
	s_addc_u32 s63, s63, s73
	global_load_dwordx4 v[18:21], v19, s[62:63]
